# P5: 13-step PR-row state copy (t==T-1 rows and sample rows) issues its 13 loads together instead of load-wait-store per step
# speedup vs baseline: 1.0334x; 1.0204x over previous
; __device__ __forceinline__ f32x4 unpack4(u32x2 u) { return (f32x4){__uint_as_float(u.x << 16), __uint_as_float(u.x & 0xffff0000u), __uint_as_float(u.y << 16), __uint_as_float(u.y & 0xffff0000u)}; }
; template <int ph>
; __device__ __forceinline__ void run_phase(const Args& args, LAS unsigned char* lds, const int G, const int bx, const bool fin = true) {
;     ...
;                 if (t == T - 1) { float* dst = out + O_PSHIFT + (size_t)b * RP;
;                     for (int c = 4 * lane; c < RP; c += 256) *(f32x4*)(dst + c) = unpack4(*(const u32x2*)(PR + (size_t)row * RP + c)); }
.LBB0_692:
	s_cmpk_lg_i32 s27, 0x7ff
	s_cbranch_scc1 .LBB0_696
	v_mad_i64_i32 v[0:1], s[28:29], s28, v75, v[64:65]
	s_mov_b64 s[28:29], 0
	v_mov_b64_e32 v[2:3], v[62:63]
	v_mov_b32_e32 v4, v17
	global_load_dwordx2 v[208:209], v[2:3], off
	global_load_dwordx2 v[210:211], v[2:3], off offset:512
	global_load_dwordx2 v[212:213], v[2:3], off offset:1024
	global_load_dwordx2 v[214:215], v[2:3], off offset:1536
	global_load_dwordx2 v[216:217], v[2:3], off offset:2048
	global_load_dwordx2 v[218:219], v[2:3], off offset:2560
	global_load_dwordx2 v[220:221], v[2:3], off offset:3072
	global_load_dwordx2 v[222:223], v[2:3], off offset:3584
	s_mov_b64 s[98:99], 0x1000
	v_lshl_add_u64 v[2:3], v[2:3], 0, s[98:99]
	global_load_dwordx2 v[224:225], v[2:3], off
	global_load_dwordx2 v[226:227], v[2:3], off offset:512
	global_load_dwordx2 v[230:231], v[2:3], off offset:1024
	global_load_dwordx2 v[232:233], v[2:3], off offset:1536
	global_load_dwordx2 v[234:235], v[2:3], off offset:2048
	s_waitcnt vmcnt(12)
	v_lshlrev_b32_e32 v6, 16, v208
	v_and_b32_e32 v7, 0xffff0000, v208
	v_lshlrev_b32_e32 v8, 16, v209
	v_and_b32_e32 v9, 0xffff0000, v209
	global_store_dwordx4 v[0:1], v[6:9], off
	s_waitcnt vmcnt(12)
	v_lshlrev_b32_e32 v10, 16, v210
	v_and_b32_e32 v11, 0xffff0000, v210
	v_lshlrev_b32_e32 v12, 16, v211
	v_and_b32_e32 v13, 0xffff0000, v211
	global_store_dwordx4 v[0:1], v[10:13], off offset:1024
	s_waitcnt vmcnt(12)
	v_lshlrev_b32_e32 v6, 16, v212
	v_and_b32_e32 v7, 0xffff0000, v212
	v_lshlrev_b32_e32 v8, 16, v213
	v_and_b32_e32 v9, 0xffff0000, v213
	global_store_dwordx4 v[0:1], v[6:9], off offset:2048
	s_waitcnt vmcnt(12)
	v_lshlrev_b32_e32 v10, 16, v214
	v_and_b32_e32 v11, 0xffff0000, v214
	v_lshlrev_b32_e32 v12, 16, v215
	v_and_b32_e32 v13, 0xffff0000, v215
	global_store_dwordx4 v[0:1], v[10:13], off offset:3072
	s_nop 1
	v_lshl_add_u64 v[0:1], v[0:1], 0, s[98:99]
	s_waitcnt vmcnt(12)
	v_lshlrev_b32_e32 v6, 16, v216
	v_and_b32_e32 v7, 0xffff0000, v216
	v_lshlrev_b32_e32 v8, 16, v217
	v_and_b32_e32 v9, 0xffff0000, v217
	global_store_dwordx4 v[0:1], v[6:9], off
	s_waitcnt vmcnt(12)
	v_lshlrev_b32_e32 v10, 16, v218
	v_and_b32_e32 v11, 0xffff0000, v218
	v_lshlrev_b32_e32 v12, 16, v219
	v_and_b32_e32 v13, 0xffff0000, v219
	global_store_dwordx4 v[0:1], v[10:13], off offset:1024
	s_waitcnt vmcnt(12)
	v_lshlrev_b32_e32 v6, 16, v220
	v_and_b32_e32 v7, 0xffff0000, v220
	v_lshlrev_b32_e32 v8, 16, v221
	v_and_b32_e32 v9, 0xffff0000, v221
	global_store_dwordx4 v[0:1], v[6:9], off offset:2048
	s_waitcnt vmcnt(12)
	v_lshlrev_b32_e32 v10, 16, v222
	v_and_b32_e32 v11, 0xffff0000, v222
	v_lshlrev_b32_e32 v12, 16, v223
	v_and_b32_e32 v13, 0xffff0000, v223
	global_store_dwordx4 v[0:1], v[10:13], off offset:3072
	s_nop 1
	v_lshl_add_u64 v[0:1], v[0:1], 0, s[98:99]
	s_waitcnt vmcnt(12)
	v_lshlrev_b32_e32 v6, 16, v224
	v_and_b32_e32 v7, 0xffff0000, v224
	v_lshlrev_b32_e32 v8, 16, v225
	v_and_b32_e32 v9, 0xffff0000, v225
	global_store_dwordx4 v[0:1], v[6:9], off
	s_waitcnt vmcnt(12)
	v_lshlrev_b32_e32 v10, 16, v226
	v_and_b32_e32 v11, 0xffff0000, v226
	v_lshlrev_b32_e32 v12, 16, v227
	v_and_b32_e32 v13, 0xffff0000, v227
	global_store_dwordx4 v[0:1], v[10:13], off offset:1024
	s_waitcnt vmcnt(12)
	v_lshlrev_b32_e32 v6, 16, v230
	v_and_b32_e32 v7, 0xffff0000, v230
	v_lshlrev_b32_e32 v8, 16, v231
	v_and_b32_e32 v9, 0xffff0000, v231
	global_store_dwordx4 v[0:1], v[6:9], off offset:2048
	s_waitcnt vmcnt(12)
	v_lshlrev_b32_e32 v10, 16, v232
	v_and_b32_e32 v11, 0xffff0000, v232
	v_lshlrev_b32_e32 v12, 16, v233
	v_and_b32_e32 v13, 0xffff0000, v233
	global_store_dwordx4 v[0:1], v[10:13], off offset:3072
	s_nop 1
	v_lshl_add_u64 v[0:1], v[0:1], 0, s[98:99]
	s_waitcnt vmcnt(12)
	v_lshlrev_b32_e32 v6, 16, v234
	v_and_b32_e32 v7, 0xffff0000, v234
	v_lshlrev_b32_e32 v8, 16, v235
	v_and_b32_e32 v9, 0xffff0000, v235
	global_store_dwordx4 v[0:1], v[6:9], off

; __device__ __forceinline__ f32x4 unpack4(u32x2 u) { return (f32x4){__uint_as_float(u.x << 16), __uint_as_float(u.x & 0xffff0000u), __uint_as_float(u.y << 16), __uint_as_float(u.y & 0xffff0000u)}; }
; __device__ __forceinline__ u32x2 pack4(f32x4 v) { u32x2 r; r.x = cvt_pk_bf16(v.x, v.y); r.y = cvt_pk_bf16(v.z, v.w); return r; }
; __device__ __forceinline__ float sigm(float x) { return 1.0f / (1.0f + __expf(-x)); }
; __device__ __forceinline__ float tanh_(float x) { float e = __expf(2.0f * x); return 1.0f - 2.0f / (e + 1.0f); }
; template <int ph>
; __device__ __forceinline__ void run_phase(const Args& args, LAS unsigned char* lds, const int G, const int bx, const bool fin = true) {
;     ...
;                 { const int c = 3072 + 4 * lane; const f32x4 p = unpack4(*(const u32x2*)(PR + (size_t)row * RP + c));
;                   const f32x4 pv = *(const f32x4*)(state_shift + (size_t)si * RP + c);
;                   const f32x4 mu = *(const f32x4*)(shift_mu + c); f32x4 xs = p + (pv - p) * mu;
;                   if (lane < 16) xs = (f32x4){tanh_(xs[0]), tanh_(xs[1]), tanh_(xs[2]), tanh_(xs[3])}; else if (lane >= 32) xs = (f32x4){sigm(xs[0]), sigm(xs[1]), sigm(xs[2]), sigm(xs[3])};
;                   *(u32x2*)(LB + (size_t)row * 256 + 4 * lane) = pack4(xs); }
; #pragma unroll
;                 for (int j = 0; j < 4; ++j) { const int c = 256 * j + 4 * lane;
;                     const f32x4 p3 = unpack4(*(const u32x2*)(PL + (size_t)row * D + c));
;                     const f32x4 p0 = *(const f32x4*)(state_conv + ((size_t)si * 3 + 0) * D + c), p1 = *(const f32x4*)(state_conv + ((size_t)si * 3 + 1) * D + c), p2 = *(const f32x4*)(state_conv + ((size_t)si * 3 + 2) * D + c);
;                     const f32x4 xc = *(const f32x4*)(conv_b + c) + *(const f32x4*)(conv_w + c) * p0 + *(const f32x4*)(conv_w + D + c) * p1 + *(const f32x4*)(conv_w + 2 * D + c) * p2 + *(const f32x4*)(conv_w + 3 * D + c) * p3;
;                     *(u32x2*)(XC + (size_t)row * D + c) = pack4(xc);
;                     *(f32x4*)(out + O_SCONV + ((size_t)si * 3 + 0) * D + c) = p1; *(f32x4*)(out + O_SCONV + ((size_t)si * 3 + 1) * D + c) = p2; *(f32x4*)(out + O_SCONV + ((size_t)si * 3 + 2) * D + c) = p3; }
.LBB0_704:
	s_or_b64 exec, exec, s[28:29]
	s_lshl_b64 s[28:29], s[0:1], 9
	v_cvt_pk_bf16_f32 v2, v2, v3
	v_cvt_pk_bf16_f32 v3, v0, v1
	v_lshl_add_u64 v[0:1], v[24:25], 0, s[28:29]
	s_mul_hi_u32 s29, s44, 0x3000
	s_mulk_i32 s44, 0x3000
	v_readlane_b32 s56, v229, 16
	v_readlane_b32 s57, v229, 17
	s_add_u32 s40, s56, s44
	s_addc_u32 s41, s57, s29
	v_lshl_add_u64 v[70:71], s[40:41], 0, v[18:19]
	global_store_dwordx2 v[0:1], v[2:3], off
	s_add_u32 s28, s11, s44
	v_add_co_u32_e32 v80, vcc, s52, v70
	s_addc_u32 s29, s13, s29
	s_lshl_b64 s[44:45], s[0:1], 11
	v_addc_co_u32_e32 v81, vcc, 0, v71, vcc
	global_load_dwordx4 v[0:3], v[30:31], off
	global_load_dwordx4 v[4:7], v[32:33], off
	global_load_dwordx4 v[8:11], v18, s[40:41]
	global_load_dwordx4 v[12:15], v[80:81], off offset:-4096
	global_load_dwordx4 v[76:79], v[34:35], off
	v_lshl_add_u64 v[96:97], v[58:59], 0, s[44:45]
	global_load_dwordx2 v[92:93], v[96:97], off
	s_nop 0
	global_load_dwordx4 v[80:83], v[80:81], off
	s_nop 0
	global_load_dwordx4 v[84:87], v[36:37], off
	global_load_dwordx4 v[88:91], v[38:39], off
	v_lshl_add_u64 v[94:95], s[28:29], 0, v[18:19]
	v_lshl_add_u64 v[100:101], v[60:61], 0, s[44:45]
	v_add_co_u32_e32 v102, vcc, s52, v94
	v_lshl_add_u64 v[98:99], v[70:71], 0, s[8:9]
	s_nop 0
	v_addc_co_u32_e32 v103, vcc, 0, v95, vcc
	v_lshl_add_u64 v[70:71], v[70:71], 0, s[14:15]
	v_lshl_add_u64 v[104:105], v[94:95], 0, s[8:9]
	v_lshl_add_u64 v[106:107], v[94:95], 0, s[14:15]
	v_readlane_b32 s58, v229, 18
	v_readlane_b32 s59, v229, 19
	v_readlane_b32 s60, v229, 20
	v_readlane_b32 s61, v229, 21
	v_readlane_b32 s62, v229, 22
	v_readlane_b32 s63, v229, 23
	v_readlane_b32 s64, v229, 24
	v_readlane_b32 s65, v229, 25
	v_readlane_b32 s66, v229, 26
	v_readlane_b32 s67, v229, 27
	v_readlane_b32 s68, v229, 28
	v_readlane_b32 s69, v229, 29
	v_readlane_b32 s70, v229, 30
	v_readlane_b32 s71, v229, 31
	s_waitcnt vmcnt(6)
	v_pk_fma_f32 v[2:3], v[10:11], v[6:7], v[2:3]
	v_pk_fma_f32 v[0:1], v[8:9], v[4:5], v[0:1]
	s_waitcnt vmcnt(4)
	v_pk_fma_f32 v[4:5], v[14:15], v[78:79], v[2:3]
	v_pk_fma_f32 v[6:7], v[12:13], v[76:77], v[0:1]
	s_waitcnt vmcnt(3)
	v_lshlrev_b32_e32 v0, 16, v92
	v_and_b32_e32 v1, 0xffff0000, v92
	v_lshlrev_b32_e32 v2, 16, v93
	v_and_b32_e32 v3, 0xffff0000, v93
	s_waitcnt vmcnt(1)
	v_pk_fma_f32 v[4:5], v[82:83], v[86:87], v[4:5]
	v_pk_fma_f32 v[6:7], v[80:81], v[84:85], v[6:7]
	s_waitcnt vmcnt(0)
	v_pk_fma_f32 v[4:5], v[90:91], v[2:3], v[4:5]
	v_pk_fma_f32 v[6:7], v[88:89], v[0:1], v[6:7]
	s_nop 0
	v_cvt_pk_bf16_f32 v6, v6, v7
	v_cvt_pk_bf16_f32 v7, v4, v5
	global_store_dwordx2 v[100:101], v[6:7], off
	global_store_dwordx4 v18, v[12:15], s[28:29]
	global_store_dwordx4 v[102:103], v[80:83], off offset:-4096
	global_store_dwordx4 v[102:103], v[0:3], off
	global_load_dwordx2 v[102:103], v[96:97], off offset:512
	s_nop 0
	global_load_dwordx4 v[0:3], v18, s[40:41] offset:1024
	global_load_dwordx4 v[4:7], v[30:31], off offset:1024
	global_load_dwordx4 v[8:11], v[32:33], off offset:1024
	global_load_dwordx4 v[12:15], v[40:41], off
	global_load_dwordx4 v[76:79], v[98:99], off offset:1024
	global_load_dwordx4 v[80:83], v[70:71], off offset:1024
	global_load_dwordx4 v[84:87], v[42:43], off
	global_load_dwordx4 v[88:91], v[44:45], off
	s_waitcnt vmcnt(5)
	v_pk_fma_f32 v[2:3], v[2:3], v[10:11], v[6:7]
	v_pk_fma_f32 v[0:1], v[0:1], v[8:9], v[4:5]
	s_waitcnt vmcnt(3)
	v_pk_fma_f32 v[2:3], v[78:79], v[14:15], v[2:3]
	v_pk_fma_f32 v[0:1], v[76:77], v[12:13], v[0:1]
	v_lshlrev_b32_e32 v92, 16, v102
	v_and_b32_e32 v93, 0xffff0000, v102
	v_lshlrev_b32_e32 v94, 16, v103
	v_and_b32_e32 v95, 0xffff0000, v103
	s_waitcnt vmcnt(1)
	v_pk_fma_f32 v[2:3], v[82:83], v[86:87], v[2:3]
	v_pk_fma_f32 v[0:1], v[80:81], v[84:85], v[0:1]
	s_waitcnt vmcnt(0)
	v_pk_fma_f32 v[2:3], v[90:91], v[94:95], v[2:3]
	v_pk_fma_f32 v[0:1], v[88:89], v[92:93], v[0:1]
	s_nop 0
	v_cvt_pk_bf16_f32 v0, v0, v1
	v_cvt_pk_bf16_f32 v1, v2, v3
	global_store_dwordx2 v[100:101], v[0:1], off offset:512
	global_store_dwordx4 v18, v[76:79], s[28:29] offset:1024
	global_store_dwordx4 v[104:105], v[80:83], off offset:1024
	global_store_dwordx4 v[106:107], v[92:95], off offset:1024
	global_load_dwordx2 v[94:95], v[96:97], off offset:1024
	s_nop 0
	global_load_dwordx4 v[0:3], v18, s[40:41] offset:2048
	global_load_dwordx4 v[4:7], v[30:31], off offset:2048
	global_load_dwordx4 v[8:11], v[32:33], off offset:2048
	global_load_dwordx4 v[12:15], v[46:47], off
	global_load_dwordx4 v[76:79], v[98:99], off offset:2048
	global_load_dwordx4 v[80:83], v[70:71], off offset:2048
	global_load_dwordx4 v[84:87], v[48:49], off
	global_load_dwordx4 v[88:91], v[50:51], off
	s_waitcnt vmcnt(8)
	v_lshlrev_b32_e32 v92, 16, v94
	v_and_b32_e32 v93, 0xffff0000, v94
	v_lshlrev_b32_e32 v94, 16, v95
	s_waitcnt vmcnt(5)
	v_pk_fma_f32 v[2:3], v[2:3], v[10:11], v[6:7]
	v_pk_fma_f32 v[0:1], v[0:1], v[8:9], v[4:5]
	s_waitcnt vmcnt(3)
	v_pk_fma_f32 v[2:3], v[78:79], v[14:15], v[2:3]
	v_pk_fma_f32 v[0:1], v[76:77], v[12:13], v[0:1]
	v_and_b32_e32 v95, 0xffff0000, v95
	s_waitcnt vmcnt(1)
	v_pk_fma_f32 v[2:3], v[82:83], v[86:87], v[2:3]
	v_pk_fma_f32 v[0:1], v[80:81], v[84:85], v[0:1]
	s_waitcnt vmcnt(0)
; __device__ __forceinline__ f32x4 unpack4(u32x2 u) { return (f32x4){__uint_as_float(u.x << 16), __uint_as_float(u.x & 0xffff0000u), __uint_as_float(u.y << 16), __uint_as_float(u.y & 0xffff0000u)}; }
; __device__ __forceinline__ u32x2 pack4(f32x4 v) { u32x2 r; r.x = cvt_pk_bf16(v.x, v.y); r.y = cvt_pk_bf16(v.z, v.w); return r; }
; template <int ph>
; __device__ __forceinline__ void run_phase(const Args& args, LAS unsigned char* lds, const int G, const int bx, const bool fin = true) {
;     ...
;                 for (int j = 0; j < 4; ++j) { const int c = 256 * j + 4 * lane;
;                     const f32x4 p3 = unpack4(*(const u32x2*)(PL + (size_t)row * D + c));
;                     const f32x4 p0 = *(const f32x4*)(state_conv + ((size_t)si * 3 + 0) * D + c), p1 = *(const f32x4*)(state_conv + ((size_t)si * 3 + 1) * D + c), p2 = *(const f32x4*)(state_conv + ((size_t)si * 3 + 2) * D + c);
;                     const f32x4 xc = *(const f32x4*)(conv_b + c) + *(const f32x4*)(conv_w + c) * p0 + *(const f32x4*)(conv_w + D + c) * p1 + *(const f32x4*)(conv_w + 2 * D + c) * p2 + *(const f32x4*)(conv_w + 3 * D + c) * p3;
;                     *(u32x2*)(XC + (size_t)row * D + c) = pack4(xc);
;                     *(f32x4*)(out + O_SCONV + ((size_t)si * 3 + 0) * D + c) = p1; *(f32x4*)(out + O_SCONV + ((size_t)si * 3 + 1) * D + c) = p2; *(f32x4*)(out + O_SCONV + ((size_t)si * 3 + 2) * D + c) = p3; }
;                 { float* dst = out + O_SSHIFT + (size_t)si * RP;
;                   for (int c = 4 * lane; c < RP; c += 256) *(f32x4*)(dst + c) = unpack4(*(const u32x2*)(PR + (size_t)row * RP + c)); }
	v_pk_fma_f32 v[2:3], v[90:91], v[94:95], v[2:3]
	v_pk_fma_f32 v[0:1], v[88:89], v[92:93], v[0:1]
	s_nop 0
	v_cvt_pk_bf16_f32 v0, v0, v1
	v_cvt_pk_bf16_f32 v1, v2, v3
	global_store_dwordx2 v[100:101], v[0:1], off offset:1024
	global_store_dwordx4 v18, v[76:79], s[28:29] offset:2048
	global_store_dwordx4 v[104:105], v[80:83], off offset:2048
	global_store_dwordx4 v[106:107], v[92:95], off offset:2048
	global_load_dwordx2 v[102:103], v[96:97], off offset:1536
	global_load_dwordx4 v[4:7], v18, s[40:41] offset:3072
	global_load_dwordx4 v[8:11], v[30:31], off offset:3072
	global_load_dwordx4 v[12:15], v[32:33], off offset:3072
	global_load_dwordx4 v[76:79], v[52:53], off
	global_load_dwordx4 v[80:83], v[98:99], off offset:3072
	global_load_dwordx4 v[84:87], v[70:71], off offset:3072
	global_load_dwordx4 v[88:91], v[54:55], off
	global_load_dwordx4 v[92:95], v[56:57], off
	v_lshl_add_u64 v[0:1], v[66:67], 0, s[26:27]
	v_mad_u64_u32 v[2:3], s[26:27], s46, v75, v[68:69]
	s_mov_b64 s[26:27], 0
	s_waitcnt vmcnt(8)
	v_lshlrev_b32_e32 v96, 16, v102
	v_and_b32_e32 v97, 0xffff0000, v102
	v_lshlrev_b32_e32 v98, 16, v103
	s_waitcnt vmcnt(5)
	v_pk_fma_f32 v[6:7], v[6:7], v[14:15], v[10:11]
	v_pk_fma_f32 v[4:5], v[4:5], v[12:13], v[8:9]
	s_waitcnt vmcnt(3)
	v_pk_fma_f32 v[6:7], v[82:83], v[78:79], v[6:7]
	v_pk_fma_f32 v[4:5], v[80:81], v[76:77], v[4:5]
	v_and_b32_e32 v99, 0xffff0000, v103
	s_waitcnt vmcnt(1)
	v_pk_fma_f32 v[6:7], v[86:87], v[90:91], v[6:7]
	v_pk_fma_f32 v[4:5], v[84:85], v[88:89], v[4:5]
	s_waitcnt vmcnt(0)
	v_pk_fma_f32 v[6:7], v[94:95], v[98:99], v[6:7]
	v_pk_fma_f32 v[4:5], v[92:93], v[96:97], v[4:5]
	s_nop 0
	v_cvt_pk_bf16_f32 v4, v4, v5
	v_cvt_pk_bf16_f32 v5, v6, v7
	global_store_dwordx2 v[100:101], v[4:5], off offset:1536
	global_store_dwordx4 v18, v[80:83], s[28:29] offset:3072
	global_store_dwordx4 v[104:105], v[84:87], off offset:3072
	global_store_dwordx4 v[106:107], v[96:99], off offset:3072
	v_mov_b32_e32 v4, v17
	global_load_dwordx2 v[208:209], v[0:1], off
	global_load_dwordx2 v[210:211], v[0:1], off offset:512
	global_load_dwordx2 v[212:213], v[0:1], off offset:1024
	global_load_dwordx2 v[214:215], v[0:1], off offset:1536
	global_load_dwordx2 v[216:217], v[0:1], off offset:2048
	global_load_dwordx2 v[218:219], v[0:1], off offset:2560
	global_load_dwordx2 v[220:221], v[0:1], off offset:3072
	global_load_dwordx2 v[222:223], v[0:1], off offset:3584
	s_mov_b64 s[98:99], 0x1000
	v_lshl_add_u64 v[0:1], v[0:1], 0, s[98:99]
	global_load_dwordx2 v[224:225], v[0:1], off
	global_load_dwordx2 v[226:227], v[0:1], off offset:512
	global_load_dwordx2 v[230:231], v[0:1], off offset:1024
	global_load_dwordx2 v[232:233], v[0:1], off offset:1536
	global_load_dwordx2 v[234:235], v[0:1], off offset:2048
	s_waitcnt vmcnt(12)
	v_lshlrev_b32_e32 v6, 16, v208
	v_and_b32_e32 v7, 0xffff0000, v208
	v_lshlrev_b32_e32 v8, 16, v209
	v_and_b32_e32 v9, 0xffff0000, v209
	global_store_dwordx4 v[2:3], v[6:9], off
	s_waitcnt vmcnt(12)
	v_lshlrev_b32_e32 v10, 16, v210
	v_and_b32_e32 v11, 0xffff0000, v210
	v_lshlrev_b32_e32 v12, 16, v211
	v_and_b32_e32 v13, 0xffff0000, v211
	global_store_dwordx4 v[2:3], v[10:13], off offset:1024
	s_waitcnt vmcnt(12)
	v_lshlrev_b32_e32 v6, 16, v212
	v_and_b32_e32 v7, 0xffff0000, v212
	v_lshlrev_b32_e32 v8, 16, v213
	v_and_b32_e32 v9, 0xffff0000, v213
	global_store_dwordx4 v[2:3], v[6:9], off offset:2048
	s_waitcnt vmcnt(12)
	v_lshlrev_b32_e32 v10, 16, v214
	v_and_b32_e32 v11, 0xffff0000, v214
	v_lshlrev_b32_e32 v12, 16, v215
	v_and_b32_e32 v13, 0xffff0000, v215
	global_store_dwordx4 v[2:3], v[10:13], off offset:3072
	s_nop 1
	v_lshl_add_u64 v[2:3], v[2:3], 0, s[98:99]
	s_waitcnt vmcnt(12)
	v_lshlrev_b32_e32 v6, 16, v216
	v_and_b32_e32 v7, 0xffff0000, v216
	v_lshlrev_b32_e32 v8, 16, v217
	v_and_b32_e32 v9, 0xffff0000, v217
	global_store_dwordx4 v[2:3], v[6:9], off
	s_waitcnt vmcnt(12)
	v_lshlrev_b32_e32 v10, 16, v218
	v_and_b32_e32 v11, 0xffff0000, v218
	v_lshlrev_b32_e32 v12, 16, v219
	v_and_b32_e32 v13, 0xffff0000, v219
	global_store_dwordx4 v[2:3], v[10:13], off offset:1024
	s_waitcnt vmcnt(12)
	v_lshlrev_b32_e32 v6, 16, v220
	v_and_b32_e32 v7, 0xffff0000, v220
	v_lshlrev_b32_e32 v8, 16, v221
	v_and_b32_e32 v9, 0xffff0000, v221
	global_store_dwordx4 v[2:3], v[6:9], off offset:2048
	s_waitcnt vmcnt(12)
	v_lshlrev_b32_e32 v10, 16, v222
	v_and_b32_e32 v11, 0xffff0000, v222
	v_lshlrev_b32_e32 v12, 16, v223
	v_and_b32_e32 v13, 0xffff0000, v223
	global_store_dwordx4 v[2:3], v[10:13], off offset:3072
	s_nop 1
	v_lshl_add_u64 v[2:3], v[2:3], 0, s[98:99]
	s_waitcnt vmcnt(12)
	v_lshlrev_b32_e32 v6, 16, v224
	v_and_b32_e32 v7, 0xffff0000, v224
	v_lshlrev_b32_e32 v8, 16, v225
	v_and_b32_e32 v9, 0xffff0000, v225
	global_store_dwordx4 v[2:3], v[6:9], off
	s_waitcnt vmcnt(12)
	v_lshlrev_b32_e32 v10, 16, v226
	v_and_b32_e32 v11, 0xffff0000, v226
	v_lshlrev_b32_e32 v12, 16, v227
	v_and_b32_e32 v13, 0xffff0000, v227
	global_store_dwordx4 v[2:3], v[10:13], off offset:1024
	s_waitcnt vmcnt(12)
	v_lshlrev_b32_e32 v6, 16, v230
	v_and_b32_e32 v7, 0xffff0000, v230
	v_lshlrev_b32_e32 v8, 16, v231
	v_and_b32_e32 v9, 0xffff0000, v231
	global_store_dwordx4 v[2:3], v[6:9], off offset:2048
	s_waitcnt vmcnt(12)
	v_lshlrev_b32_e32 v10, 16, v232
	v_and_b32_e32 v11, 0xffff0000, v232
	v_lshlrev_b32_e32 v12, 16, v233
	v_and_b32_e32 v13, 0xffff0000, v233
	global_store_dwordx4 v[2:3], v[10:13], off offset:3072
	s_nop 1
	v_lshl_add_u64 v[2:3], v[2:3], 0, s[98:99]
	s_waitcnt vmcnt(12)
	v_lshlrev_b32_e32 v6, 16, v234
	v_and_b32_e32 v7, 0xffff0000, v234
	v_lshlrev_b32_e32 v8, 16, v235
	v_and_b32_e32 v9, 0xffff0000, v235
	global_store_dwordx4 v[2:3], v[6:9], off
	s_branch .LBB0_682
